# gate-tile stores sc0 sc1 (system-scope write-through); + no entry grid.sync
# baseline (speedup 1.0000x reference)
; __device__ __forceinline__ float sigm(float v) { return __builtin_amdgcn_rcpf(1.0f + __builtin_amdgcn_exp2f(-LOG2E * v)); }
; __device__ __forceinline__ unsigned cvt_pk_bf16(float lo, float hi) { f32x2_t v = {lo, hi}; bf16x2_t b = __builtin_convertvector(v, bf16x2_t); return __builtin_bit_cast(unsigned, b); }
; template <int MODE> __device__ __forceinline__ float actf(float v) {
;     if (MODE == 1) return v * sigm(v);
;     if (MODE == 2) return fminf(1.0f + __builtin_amdgcn_exp2f(-LOG2E * v), 1e30f);
;     template <int MODE> __device__ __forceinline__ void run(const f32x4 (&acc)[2][2][4][2], const Unit& u, int wr, int wc, int fr, int fq) const {
;     ...
;         char* base = (MODE == 2) ? (char*)(O + (size_t)6 * ((size_t)MTOK * 512)) + ((size_t)(((pn - 12) * 128 + u.pm) * 8 + wid__)) * 16384
;                                  : (char*)(O + (size_t)t * ((size_t)MTOK * 512) + (size_t)u.pm * BM * 512 + (colt & 511));
;         unsigned off0 = (MODE == 2) ? (unsigned)((t__ & 63) * 16) : (unsigned)((wr * 64 + fr) * 512 + wc * 32 + 8 * fq) * 2u; asm volatile("" : "+v"(off0));
; #pragma unroll
;         for (int bj = 0; bj < 2; ++bj) {
; #pragma unroll
;             for (int ai = 0; ai < 2; ++ai)
; #pragma unroll
;                 for (int m = 0; m < 4; ++m) { const unsigned off = off0 + ((MODE == 2) ? (unsigned)(((ai * 4 + m) * 2 + bj) * 1024) : (unsigned)((ai * HALF + m * 16) * 512 + bj * HALF) * 2u);
;                     const f32x4 v0 = acc[ai][bj][m][0], v1 = acc[ai][bj][m][1];
;                     u32x4 w; w.x = cvt_pk_bf16(actf<MODE>(v0[0]), actf<MODE>(v0[1])); w.y = cvt_pk_bf16(actf<MODE>(v0[2]), actf<MODE>(v0[3]));
;                     w.z = cvt_pk_bf16(actf<MODE>(v1[0]), actf<MODE>(v1[1])); w.w = cvt_pk_bf16(actf<MODE>(v1[2]), actf<MODE>(v1[3]));
;                     *(u32x4*)(base + off) = w; }
.LBB0_403:
	v_mul_f32_e32 v12, 0xbfb8aa3b, v12
	v_mul_f32_e32 v13, 0xbfb8aa3b, v13
	v_exp_f32_e32 v12, v12
	v_exp_f32_e32 v13, v13
	v_mul_f32_e32 v14, 0xbfb8aa3b, v14
	v_mul_f32_e32 v15, 0xbfb8aa3b, v15
	v_mul_f32_e32 v8, 0xbfb8aa3b, v8
	v_mul_f32_e32 v9, 0xbfb8aa3b, v9
	v_exp_f32_e32 v14, v14
	v_exp_f32_e32 v15, v15
	v_exp_f32_e32 v8, v8
	v_exp_f32_e32 v9, v9
	v_mul_f32_e32 v10, 0xbfb8aa3b, v10
	v_mul_f32_e32 v11, 0xbfb8aa3b, v11
	v_add_f32_e32 v12, 1.0, v12
	v_add_f32_e32 v13, 1.0, v13
	v_exp_f32_e32 v10, v10
	v_exp_f32_e32 v11, v11
	v_mul_f32_e32 v76, 0xbfb8aa3b, v76
	v_mul_f32_e32 v77, 0xbfb8aa3b, v77
	v_min_f32_e32 v12, 0x7149f2ca, v12
	v_min_f32_e32 v13, 0x7149f2ca, v13
	v_exp_f32_e32 v76, v76
	v_exp_f32_e32 v77, v77
	v_cvt_pk_bf16_f32 v12, v12, v13
	v_add_f32_e32 v13, 1.0, v14
	v_add_f32_e32 v14, 1.0, v15
	v_add_f32_e32 v8, 1.0, v8
	v_add_f32_e32 v9, 1.0, v9
	v_mul_f32_e32 v78, 0xbfb8aa3b, v78
	v_mul_f32_e32 v79, 0xbfb8aa3b, v79
	v_mul_f32_e32 v72, 0xbfb8aa3b, v72
	v_mul_f32_e32 v73, 0xbfb8aa3b, v73
	v_min_f32_e32 v13, 0x7149f2ca, v13
	v_min_f32_e32 v14, 0x7149f2ca, v14
	v_min_f32_e32 v8, 0x7149f2ca, v8
	v_min_f32_e32 v9, 0x7149f2ca, v9
	v_mov_b32_e32 v142, v212
	s_lshl_b32 s60, s72, 7
	v_exp_f32_e32 v78, v78
	v_exp_f32_e32 v79, v79
	v_exp_f32_e32 v72, v72
	v_exp_f32_e32 v73, v73
	v_cvt_pk_bf16_f32 v13, v13, v14
	v_cvt_pk_bf16_f32 v14, v8, v9
	v_add_f32_e32 v8, 1.0, v10
	v_add_f32_e32 v9, 1.0, v11
	s_add_i32 s60, s60, s54
	v_readfirstlane_b32 s55, v142
	v_mul_f32_e32 v74, 0xbfb8aa3b, v74
	v_mul_f32_e32 v75, 0xbfb8aa3b, v75
	v_min_f32_e32 v8, 0x7149f2ca, v8
	v_min_f32_e32 v9, 0x7149f2ca, v9
	s_ashr_i32 s55, s55, 6
	s_lshl_b32 s54, s60, 3
	v_add_f32_e32 v76, 1.0, v76
	v_add_f32_e32 v77, 1.0, v77
	v_exp_f32_e32 v74, v74
	v_exp_f32_e32 v75, v75
	v_cvt_pk_bf16_f32 v15, v8, v9
	v_mul_f32_e32 v8, 0xbfb8aa3b, v68
	v_mul_f32_e32 v9, 0xbfb8aa3b, v69
	s_add_i32 s54, s54, s55
	v_min_f32_e32 v76, 0x7149f2ca, v76
	v_min_f32_e32 v77, 0x7149f2ca, v77
	v_exp_f32_e32 v8, v8
	v_exp_f32_e32 v9, v9
	s_addk_i32 s54, 0xd000
	v_cvt_pk_bf16_f32 v76, v76, v77
	v_add_f32_e32 v77, 1.0, v78
	v_add_f32_e32 v78, 1.0, v79
	v_add_f32_e32 v72, 1.0, v72
	v_add_f32_e32 v73, 1.0, v73
	v_mul_f32_e32 v10, 0xbfb8aa3b, v70
	v_mul_f32_e32 v11, 0xbfb8aa3b, v71
	s_ashr_i32 s55, s54, 31
	v_min_f32_e32 v77, 0x7149f2ca, v77
	v_min_f32_e32 v78, 0x7149f2ca, v78
	v_min_f32_e32 v72, 0x7149f2ca, v72
	v_min_f32_e32 v73, 0x7149f2ca, v73
	v_exp_f32_e32 v10, v10
	v_exp_f32_e32 v11, v11
	s_lshl_b64 s[54:55], s[54:55], 14
	v_lshlrev_b32_e32 v142, 4, v142
	v_cvt_pk_bf16_f32 v77, v77, v78
	v_cvt_pk_bf16_f32 v78, v72, v73
	v_add_f32_e32 v72, 1.0, v74
	v_add_f32_e32 v73, 1.0, v75
	s_add_u32 s54, s33, s54
	v_and_b32_e32 v142, 0x3f0, v142
	v_min_f32_e32 v72, 0x7149f2ca, v72
	v_min_f32_e32 v73, 0x7149f2ca, v73
	v_add_f32_e32 v8, 1.0, v8
	v_add_f32_e32 v9, 1.0, v9
	s_addc_u32 s55, s37, s55
	v_cvt_pk_bf16_f32 v79, v72, v73
	v_add_u32_e32 v72, 0x3800, v142
	v_min_f32_e32 v8, 0x7149f2ca, v8
	v_min_f32_e32 v9, 0x7149f2ca, v9
	v_mul_f32_e32 v126, 0xbfb8aa3b, v126
	v_mul_f32_e32 v127, 0xbfb8aa3b, v127
	v_mul_f32_e32 v118, 0xbfb8aa3b, v118
	v_mul_f32_e32 v119, 0xbfb8aa3b, v119
	v_mul_f32_e32 v110, 0xbfb8aa3b, v110
	v_mul_f32_e32 v111, 0xbfb8aa3b, v111
	v_mul_f32_e32 v102, 0xbfb8aa3b, v102
	v_mul_f32_e32 v103, 0xbfb8aa3b, v103
	v_mul_f32_e32 v92, 0xbfb8aa3b, v92
	v_mul_f32_e32 v93, 0xbfb8aa3b, v93
	v_mul_f32_e32 v84, 0xbfb8aa3b, v84
	v_mul_f32_e32 v85, 0xbfb8aa3b, v85
	global_store_dwordx4 v72, v[12:15], s[54:55] sc0 sc1
	v_cvt_pk_bf16_f32 v8, v8, v9
	v_add_f32_e32 v9, 1.0, v10
	v_add_f32_e32 v10, 1.0, v11
	v_mul_f32_e32 v11, 0xbfb8aa3b, v64
	v_mul_f32_e32 v13, 0xbfb8aa3b, v65
	v_exp_f32_e32 v126, v126
	v_exp_f32_e32 v127, v127
	v_exp_f32_e32 v118, v118
	v_exp_f32_e32 v119, v119
	v_exp_f32_e32 v110, v110
	v_exp_f32_e32 v111, v111
	v_exp_f32_e32 v102, v102
	v_exp_f32_e32 v103, v103
	v_exp_f32_e32 v92, v92
	v_exp_f32_e32 v93, v93
	v_exp_f32_e32 v84, v84
	v_exp_f32_e32 v85, v85
	v_exp_f32_e32 v11, v11
	v_exp_f32_e32 v13, v13
	v_mul_f32_e32 v128, 0xbfb8aa3b, v128
	v_mul_f32_e32 v129, 0xbfb8aa3b, v129
	v_mul_f32_e32 v122, 0xbfb8aa3b, v122
	v_mul_f32_e32 v123, 0xbfb8aa3b, v123
	v_mul_f32_e32 v120, 0xbfb8aa3b, v120
	v_mul_f32_e32 v121, 0xbfb8aa3b, v121
	v_mul_f32_e32 v114, 0xbfb8aa3b, v114
	v_mul_f32_e32 v115, 0xbfb8aa3b, v115
	v_mul_f32_e32 v112, 0xbfb8aa3b, v112
	v_mul_f32_e32 v113, 0xbfb8aa3b, v113
	v_mul_f32_e32 v106, 0xbfb8aa3b, v106
	v_mul_f32_e32 v107, 0xbfb8aa3b, v107
	v_mul_f32_e32 v104, 0xbfb8aa3b, v104
	v_mul_f32_e32 v105, 0xbfb8aa3b, v105
	v_mul_f32_e32 v98, 0xbfb8aa3b, v98
	v_mul_f32_e32 v99, 0xbfb8aa3b, v99
	v_mul_f32_e32 v94, 0xbfb8aa3b, v94
	v_mul_f32_e32 v95, 0xbfb8aa3b, v95
	v_mul_f32_e32 v88, 0xbfb8aa3b, v88
	v_mul_f32_e32 v89, 0xbfb8aa3b, v89
	v_mul_f32_e32 v86, 0xbfb8aa3b, v86
	v_mul_f32_e32 v87, 0xbfb8aa3b, v87
	v_mul_f32_e32 v80, 0xbfb8aa3b, v80
	v_mul_f32_e32 v81, 0xbfb8aa3b, v81
	v_exp_f32_e32 v128, v128
	v_exp_f32_e32 v129, v129
	v_exp_f32_e32 v122, v122
	v_exp_f32_e32 v123, v123
	v_exp_f32_e32 v120, v120
	v_exp_f32_e32 v121, v121
	v_exp_f32_e32 v114, v114
	v_exp_f32_e32 v115, v115
	v_exp_f32_e32 v112, v112
	v_exp_f32_e32 v113, v113
	v_exp_f32_e32 v106, v106
	v_exp_f32_e32 v107, v107
	v_exp_f32_e32 v104, v104
	v_exp_f32_e32 v105, v105
	v_exp_f32_e32 v98, v98
	v_exp_f32_e32 v99, v99
	v_exp_f32_e32 v94, v94
	v_exp_f32_e32 v95, v95
	v_exp_f32_e32 v88, v88
	v_exp_f32_e32 v89, v89
	v_exp_f32_e32 v86, v86
	v_exp_f32_e32 v87, v87
	v_exp_f32_e32 v80, v80
	v_exp_f32_e32 v81, v81
	v_mul_f32_e32 v124, 0xbfb8aa3b, v124
	v_mul_f32_e32 v125, 0xbfb8aa3b, v125
	v_mul_f32_e32 v116, 0xbfb8aa3b, v116
; __device__ __forceinline__ unsigned cvt_pk_bf16(float lo, float hi) { f32x2_t v = {lo, hi}; bf16x2_t b = __builtin_convertvector(v, bf16x2_t); return __builtin_bit_cast(unsigned, b); }
;     template <int MODE> __device__ __forceinline__ void run(const f32x4 (&acc)[2][2][4][2], const Unit& u, int wr, int wc, int fr, int fq) const {
;     ...
;                 for (int m = 0; m < 4; ++m) { const unsigned off = off0 + ((MODE == 2) ? (unsigned)(((ai * 4 + m) * 2 + bj) * 1024) : (unsigned)((ai * HALF + m * 16) * 512 + bj * HALF) * 2u);
;                     const f32x4 v0 = acc[ai][bj][m][0], v1 = acc[ai][bj][m][1];
;                     u32x4 w; w.x = cvt_pk_bf16(actf<MODE>(v0[0]), actf<MODE>(v0[1])); w.y = cvt_pk_bf16(actf<MODE>(v0[2]), actf<MODE>(v0[3]));
;                     w.z = cvt_pk_bf16(actf<MODE>(v1[0]), actf<MODE>(v1[1])); w.w = cvt_pk_bf16(actf<MODE>(v1[2]), actf<MODE>(v1[3]));
;                     *(u32x4*)(base + off) = w; }
	v_mul_f32_e32 v117, 0xbfb8aa3b, v117
	v_mul_f32_e32 v108, 0xbfb8aa3b, v108
	v_mul_f32_e32 v109, 0xbfb8aa3b, v109
	v_mul_f32_e32 v100, 0xbfb8aa3b, v100
	v_mul_f32_e32 v101, 0xbfb8aa3b, v101
	v_mul_f32_e32 v90, 0xbfb8aa3b, v90
	v_mul_f32_e32 v91, 0xbfb8aa3b, v91
	v_mul_f32_e32 v82, 0xbfb8aa3b, v82
	v_mul_f32_e32 v83, 0xbfb8aa3b, v83
	v_min_f32_e32 v9, 0x7149f2ca, v9
	v_min_f32_e32 v10, 0x7149f2ca, v10
	v_add_f32_e32 v126, 1.0, v126
	v_add_f32_e32 v127, 1.0, v127
	v_exp_f32_e32 v124, v124
	v_exp_f32_e32 v125, v125
	v_add_f32_e32 v118, 1.0, v118
	v_add_f32_e32 v119, 1.0, v119
	v_exp_f32_e32 v116, v116
	v_exp_f32_e32 v117, v117
	v_add_f32_e32 v110, 1.0, v110
	v_add_f32_e32 v111, 1.0, v111
	v_exp_f32_e32 v108, v108
	v_exp_f32_e32 v109, v109
	v_add_f32_e32 v102, 1.0, v102
	v_add_f32_e32 v103, 1.0, v103
	v_exp_f32_e32 v100, v100
	v_exp_f32_e32 v101, v101
	v_add_f32_e32 v92, 1.0, v92
	v_add_f32_e32 v93, 1.0, v93
	v_exp_f32_e32 v90, v90
	v_exp_f32_e32 v91, v91
	v_add_f32_e32 v84, 1.0, v84
	v_add_f32_e32 v85, 1.0, v85
	v_exp_f32_e32 v82, v82
	v_exp_f32_e32 v83, v83
	v_cvt_pk_bf16_f32 v9, v9, v10
	v_add_f32_e32 v10, 1.0, v11
	v_add_f32_e32 v11, 1.0, v13
	v_mul_f32_e32 v13, 0xbfb8aa3b, v66
	v_mul_f32_e32 v14, 0xbfb8aa3b, v67
	v_min_f32_e32 v126, 0x7149f2ca, v126
	v_min_f32_e32 v127, 0x7149f2ca, v127
	v_min_f32_e32 v118, 0x7149f2ca, v118
	v_min_f32_e32 v119, 0x7149f2ca, v119
	v_min_f32_e32 v110, 0x7149f2ca, v110
	v_min_f32_e32 v111, 0x7149f2ca, v111
	v_min_f32_e32 v102, 0x7149f2ca, v102
	v_min_f32_e32 v103, 0x7149f2ca, v103
	v_min_f32_e32 v92, 0x7149f2ca, v92
	v_min_f32_e32 v93, 0x7149f2ca, v93
	v_min_f32_e32 v84, 0x7149f2ca, v84
	v_min_f32_e32 v85, 0x7149f2ca, v85
	v_exp_f32_e32 v13, v13
	v_exp_f32_e32 v14, v14
	v_cvt_pk_bf16_f32 v126, v126, v127
	v_add_f32_e32 v127, 1.0, v128
	v_add_f32_e32 v128, 1.0, v129
	v_add_f32_e32 v122, 1.0, v122
	v_add_f32_e32 v123, 1.0, v123
	v_cvt_pk_bf16_f32 v118, v118, v119
	v_add_f32_e32 v119, 1.0, v120
	v_add_f32_e32 v120, 1.0, v121
	v_add_f32_e32 v114, 1.0, v114
	v_add_f32_e32 v115, 1.0, v115
	v_cvt_pk_bf16_f32 v110, v110, v111
	v_add_f32_e32 v111, 1.0, v112
	v_add_f32_e32 v112, 1.0, v113
	v_add_f32_e32 v106, 1.0, v106
	v_add_f32_e32 v107, 1.0, v107
	v_cvt_pk_bf16_f32 v102, v102, v103
	v_add_f32_e32 v103, 1.0, v104
	v_add_f32_e32 v104, 1.0, v105
	v_add_f32_e32 v98, 1.0, v98
	v_add_f32_e32 v99, 1.0, v99
	v_cvt_pk_bf16_f32 v92, v92, v93
	v_add_f32_e32 v93, 1.0, v94
	v_add_f32_e32 v94, 1.0, v95
	v_add_f32_e32 v88, 1.0, v88
	v_add_f32_e32 v89, 1.0, v89
	v_cvt_pk_bf16_f32 v84, v84, v85
	v_add_f32_e32 v85, 1.0, v86
	v_add_f32_e32 v86, 1.0, v87
	v_add_f32_e32 v80, 1.0, v80
	v_add_f32_e32 v81, 1.0, v81
	v_min_f32_e32 v127, 0x7149f2ca, v127
	v_min_f32_e32 v128, 0x7149f2ca, v128
	v_min_f32_e32 v122, 0x7149f2ca, v122
	v_min_f32_e32 v123, 0x7149f2ca, v123
	v_min_f32_e32 v119, 0x7149f2ca, v119
	v_min_f32_e32 v120, 0x7149f2ca, v120
	v_min_f32_e32 v114, 0x7149f2ca, v114
	v_min_f32_e32 v115, 0x7149f2ca, v115
	v_min_f32_e32 v111, 0x7149f2ca, v111
	v_min_f32_e32 v112, 0x7149f2ca, v112
	v_min_f32_e32 v106, 0x7149f2ca, v106
	v_min_f32_e32 v107, 0x7149f2ca, v107
	v_min_f32_e32 v103, 0x7149f2ca, v103
	v_min_f32_e32 v104, 0x7149f2ca, v104
	v_min_f32_e32 v98, 0x7149f2ca, v98
	v_min_f32_e32 v99, 0x7149f2ca, v99
	v_min_f32_e32 v93, 0x7149f2ca, v93
	v_min_f32_e32 v94, 0x7149f2ca, v94
	v_min_f32_e32 v88, 0x7149f2ca, v88
	v_min_f32_e32 v89, 0x7149f2ca, v89
	v_min_f32_e32 v85, 0x7149f2ca, v85
	v_min_f32_e32 v86, 0x7149f2ca, v86
	v_min_f32_e32 v80, 0x7149f2ca, v80
	v_min_f32_e32 v81, 0x7149f2ca, v81
	v_cvt_pk_bf16_f32 v127, v127, v128
	v_cvt_pk_bf16_f32 v128, v122, v123
	v_add_f32_e32 v122, 1.0, v124
	v_add_f32_e32 v123, 1.0, v125
	v_cvt_pk_bf16_f32 v119, v119, v120
	v_cvt_pk_bf16_f32 v120, v114, v115
	v_add_f32_e32 v114, 1.0, v116
	v_add_f32_e32 v115, 1.0, v117
	v_cvt_pk_bf16_f32 v111, v111, v112
	v_cvt_pk_bf16_f32 v112, v106, v107
	v_add_f32_e32 v106, 1.0, v108
	v_add_f32_e32 v107, 1.0, v109
	v_cvt_pk_bf16_f32 v103, v103, v104
	v_cvt_pk_bf16_f32 v104, v98, v99
	v_add_f32_e32 v98, 1.0, v100
	v_add_f32_e32 v99, 1.0, v101
	v_cvt_pk_bf16_f32 v93, v93, v94
	v_cvt_pk_bf16_f32 v94, v88, v89
	v_add_f32_e32 v88, 1.0, v90
	v_add_f32_e32 v89, 1.0, v91
	v_cvt_pk_bf16_f32 v85, v85, v86
	v_cvt_pk_bf16_f32 v86, v80, v81
	v_add_f32_e32 v80, 1.0, v82
	v_add_f32_e32 v81, 1.0, v83
	v_min_f32_e32 v10, 0x7149f2ca, v10
	v_min_f32_e32 v11, 0x7149f2ca, v11
	v_min_f32_e32 v122, 0x7149f2ca, v122
	v_min_f32_e32 v123, 0x7149f2ca, v123
	v_min_f32_e32 v114, 0x7149f2ca, v114
	v_min_f32_e32 v115, 0x7149f2ca, v115
	v_min_f32_e32 v106, 0x7149f2ca, v106
	v_min_f32_e32 v107, 0x7149f2ca, v107
	v_min_f32_e32 v98, 0x7149f2ca, v98
	v_min_f32_e32 v99, 0x7149f2ca, v99
	v_min_f32_e32 v88, 0x7149f2ca, v88
	v_min_f32_e32 v89, 0x7149f2ca, v89
	v_min_f32_e32 v80, 0x7149f2ca, v80
	v_min_f32_e32 v81, 0x7149f2ca, v81
	v_cvt_pk_bf16_f32 v10, v10, v11
	v_add_f32_e32 v11, 1.0, v13
	v_add_f32_e32 v13, 1.0, v14
	v_cvt_pk_bf16_f32 v129, v122, v123
	v_add_u32_e32 v122, 0x800, v142
	v_cvt_pk_bf16_f32 v121, v114, v115
	v_add_u32_e32 v114, 0x1000, v142
	v_cvt_pk_bf16_f32 v113, v106, v107
	v_add_u32_e32 v106, 0x1800, v142
	v_cvt_pk_bf16_f32 v105, v98, v99
	v_add_u32_e32 v98, 0x2000, v142
	v_cvt_pk_bf16_f32 v95, v88, v89
	v_add_u32_e32 v88, 0x2800, v142
	v_cvt_pk_bf16_f32 v87, v80, v81
	v_add_u32_e32 v80, 0x3000, v142
	v_min_f32_e32 v11, 0x7149f2ca, v11
	v_min_f32_e32 v13, 0x7149f2ca, v13
	global_store_dwordx4 v142, v[126:129], s[54:55] sc0 sc1
	global_store_dwordx4 v122, v[118:121], s[54:55] sc0 sc1
	global_store_dwordx4 v114, v[110:113], s[54:55] sc0 sc1
	global_store_dwordx4 v106, v[102:105], s[54:55] sc0 sc1
; __device__ __forceinline__ unsigned cvt_pk_bf16(float lo, float hi) { f32x2_t v = {lo, hi}; bf16x2_t b = __builtin_convertvector(v, bf16x2_t); return __builtin_bit_cast(unsigned, b); }
;     template <int MODE> __device__ __forceinline__ void run(const f32x4 (&acc)[2][2][4][2], const Unit& u, int wr, int wc, int fr, int fq) const {
;     ...
;                 for (int m = 0; m < 4; ++m) { const unsigned off = off0 + ((MODE == 2) ? (unsigned)(((ai * 4 + m) * 2 + bj) * 1024) : (unsigned)((ai * HALF + m * 16) * 512 + bj * HALF) * 2u);
;                     const f32x4 v0 = acc[ai][bj][m][0], v1 = acc[ai][bj][m][1];
;                     u32x4 w; w.x = cvt_pk_bf16(actf<MODE>(v0[0]), actf<MODE>(v0[1])); w.y = cvt_pk_bf16(actf<MODE>(v0[2]), actf<MODE>(v0[3]));
;                     w.z = cvt_pk_bf16(actf<MODE>(v1[0]), actf<MODE>(v1[1])); w.w = cvt_pk_bf16(actf<MODE>(v1[2]), actf<MODE>(v1[3]));
;                     *(u32x4*)(base + off) = w; }
	global_store_dwordx4 v98, v[92:95], s[54:55] sc0 sc1
	global_store_dwordx4 v88, v[84:87], s[54:55] sc0 sc1
	global_store_dwordx4 v80, v[76:79], s[54:55] sc0 sc1
	v_add_u32_e32 v12, 0x400, v142
	v_cvt_pk_bf16_f32 v11, v11, v13
	global_store_dwordx4 v12, v[8:11], s[54:55] sc0 sc1
	v_mul_f32_e32 v13, 0xbfb8aa3b, v57
	v_exp_f32_e32 v13, v13
	v_mul_f32_e32 v8, 0xbfb8aa3b, v60
	v_mul_f32_e32 v9, 0xbfb8aa3b, v61
	v_exp_f32_e32 v8, v8
	v_exp_f32_e32 v9, v9
	v_mul_f32_e32 v10, 0xbfb8aa3b, v62
	v_mul_f32_e32 v11, 0xbfb8aa3b, v63
	v_exp_f32_e32 v10, v10
	v_exp_f32_e32 v11, v11
	v_add_f32_e32 v8, 1.0, v8
	v_add_f32_e32 v9, 1.0, v9
	v_min_f32_e32 v8, 0x7149f2ca, v8
	v_min_f32_e32 v9, 0x7149f2ca, v9
	v_cvt_pk_bf16_f32 v8, v8, v9
	v_add_f32_e32 v9, 1.0, v10
	v_add_f32_e32 v10, 1.0, v11
	v_mul_f32_e32 v11, 0xbfb8aa3b, v56
	v_exp_f32_e32 v11, v11
	v_min_f32_e32 v9, 0x7149f2ca, v9
	v_min_f32_e32 v10, 0x7149f2ca, v10
	v_cvt_pk_bf16_f32 v9, v9, v10
	v_add_f32_e32 v10, 1.0, v11
	v_add_f32_e32 v11, 1.0, v13
	v_mul_f32_e32 v13, 0xbfb8aa3b, v58
	v_mul_f32_e32 v14, 0xbfb8aa3b, v59
	v_exp_f32_e32 v13, v13
	v_exp_f32_e32 v14, v14
	v_min_f32_e32 v10, 0x7149f2ca, v10
	v_min_f32_e32 v11, 0x7149f2ca, v11
	v_cvt_pk_bf16_f32 v10, v10, v11
	v_add_f32_e32 v11, 1.0, v13
	v_add_f32_e32 v13, 1.0, v14
	v_min_f32_e32 v11, 0x7149f2ca, v11
	v_min_f32_e32 v13, 0x7149f2ca, v13
	v_add_u32_e32 v12, 0xc00, v142
	v_cvt_pk_bf16_f32 v11, v11, v13
	global_store_dwordx4 v12, v[8:11], s[54:55] sc0 sc1
	v_mul_f32_e32 v13, 0xbfb8aa3b, v49
	v_exp_f32_e32 v13, v13
	v_mul_f32_e32 v8, 0xbfb8aa3b, v52
	v_mul_f32_e32 v9, 0xbfb8aa3b, v53
	v_exp_f32_e32 v8, v8
	v_exp_f32_e32 v9, v9
	v_mul_f32_e32 v10, 0xbfb8aa3b, v54
	v_mul_f32_e32 v11, 0xbfb8aa3b, v55
	v_exp_f32_e32 v10, v10
	v_exp_f32_e32 v11, v11
	v_add_f32_e32 v8, 1.0, v8
	v_add_f32_e32 v9, 1.0, v9
	v_min_f32_e32 v8, 0x7149f2ca, v8
	v_min_f32_e32 v9, 0x7149f2ca, v9
	v_cvt_pk_bf16_f32 v8, v8, v9
	v_add_f32_e32 v9, 1.0, v10
	v_add_f32_e32 v10, 1.0, v11
	v_mul_f32_e32 v11, 0xbfb8aa3b, v48
	v_exp_f32_e32 v11, v11
	v_min_f32_e32 v9, 0x7149f2ca, v9
	v_min_f32_e32 v10, 0x7149f2ca, v10
	v_cvt_pk_bf16_f32 v9, v9, v10
	v_add_f32_e32 v10, 1.0, v11
	v_add_f32_e32 v11, 1.0, v13
	v_mul_f32_e32 v13, 0xbfb8aa3b, v50
	v_mul_f32_e32 v14, 0xbfb8aa3b, v51
	v_exp_f32_e32 v13, v13
	v_exp_f32_e32 v14, v14
	v_min_f32_e32 v10, 0x7149f2ca, v10
	v_min_f32_e32 v11, 0x7149f2ca, v11
	v_cvt_pk_bf16_f32 v10, v10, v11
	v_add_f32_e32 v11, 1.0, v13
	v_add_f32_e32 v13, 1.0, v14
	v_min_f32_e32 v11, 0x7149f2ca, v11
	v_min_f32_e32 v13, 0x7149f2ca, v13
	v_add_u32_e32 v12, 0x1400, v142
	v_cvt_pk_bf16_f32 v11, v11, v13
	global_store_dwordx4 v12, v[8:11], s[54:55] sc0 sc1
	v_mul_f32_e32 v13, 0xbfb8aa3b, v41
	v_exp_f32_e32 v13, v13
	v_mul_f32_e32 v8, 0xbfb8aa3b, v44
	v_mul_f32_e32 v9, 0xbfb8aa3b, v45
	v_exp_f32_e32 v8, v8
	v_exp_f32_e32 v9, v9
	v_mul_f32_e32 v10, 0xbfb8aa3b, v46
	v_mul_f32_e32 v11, 0xbfb8aa3b, v47
	v_exp_f32_e32 v10, v10
	v_exp_f32_e32 v11, v11
	v_add_f32_e32 v8, 1.0, v8
	v_add_f32_e32 v9, 1.0, v9
	v_min_f32_e32 v8, 0x7149f2ca, v8
	v_min_f32_e32 v9, 0x7149f2ca, v9
	v_cvt_pk_bf16_f32 v8, v8, v9
	v_add_f32_e32 v9, 1.0, v10
	v_add_f32_e32 v10, 1.0, v11
	v_mul_f32_e32 v11, 0xbfb8aa3b, v40
	v_exp_f32_e32 v11, v11
	v_min_f32_e32 v9, 0x7149f2ca, v9
	v_min_f32_e32 v10, 0x7149f2ca, v10
	v_cvt_pk_bf16_f32 v9, v9, v10
	v_add_f32_e32 v10, 1.0, v11
	v_add_f32_e32 v11, 1.0, v13
	v_mul_f32_e32 v13, 0xbfb8aa3b, v42
	v_mul_f32_e32 v14, 0xbfb8aa3b, v43
	v_exp_f32_e32 v13, v13
	v_exp_f32_e32 v14, v14
	v_min_f32_e32 v10, 0x7149f2ca, v10
	v_min_f32_e32 v11, 0x7149f2ca, v11
	v_cvt_pk_bf16_f32 v10, v10, v11
	v_add_f32_e32 v11, 1.0, v13
	v_add_f32_e32 v13, 1.0, v14
	v_min_f32_e32 v11, 0x7149f2ca, v11
	v_min_f32_e32 v13, 0x7149f2ca, v13
	v_add_u32_e32 v12, 0x1c00, v142
	v_cvt_pk_bf16_f32 v11, v11, v13
	global_store_dwordx4 v12, v[8:11], s[54:55] sc0 sc1
	v_mul_f32_e32 v13, 0xbfb8aa3b, v33
	v_exp_f32_e32 v13, v13
	v_mul_f32_e32 v8, 0xbfb8aa3b, v36
	v_mul_f32_e32 v9, 0xbfb8aa3b, v37
	v_exp_f32_e32 v8, v8
	v_exp_f32_e32 v9, v9
	v_mul_f32_e32 v10, 0xbfb8aa3b, v38
	v_mul_f32_e32 v11, 0xbfb8aa3b, v39
	v_exp_f32_e32 v10, v10
	v_exp_f32_e32 v11, v11
	v_add_f32_e32 v8, 1.0, v8
	v_add_f32_e32 v9, 1.0, v9
	v_min_f32_e32 v8, 0x7149f2ca, v8
	v_min_f32_e32 v9, 0x7149f2ca, v9
	v_cvt_pk_bf16_f32 v8, v8, v9
; __device__ __forceinline__ unsigned cvt_pk_bf16(float lo, float hi) { f32x2_t v = {lo, hi}; bf16x2_t b = __builtin_convertvector(v, bf16x2_t); return __builtin_bit_cast(unsigned, b); }
;     template <int MODE> __device__ __forceinline__ void run(const f32x4 (&acc)[2][2][4][2], const Unit& u, int wr, int wc, int fr, int fq) const {
;     ...
;                 for (int m = 0; m < 4; ++m) { const unsigned off = off0 + ((MODE == 2) ? (unsigned)(((ai * 4 + m) * 2 + bj) * 1024) : (unsigned)((ai * HALF + m * 16) * 512 + bj * HALF) * 2u);
;                     const f32x4 v0 = acc[ai][bj][m][0], v1 = acc[ai][bj][m][1];
;                     u32x4 w; w.x = cvt_pk_bf16(actf<MODE>(v0[0]), actf<MODE>(v0[1])); w.y = cvt_pk_bf16(actf<MODE>(v0[2]), actf<MODE>(v0[3]));
;                     w.z = cvt_pk_bf16(actf<MODE>(v1[0]), actf<MODE>(v1[1])); w.w = cvt_pk_bf16(actf<MODE>(v1[2]), actf<MODE>(v1[3]));
;                     *(u32x4*)(base + off) = w; }
	v_add_f32_e32 v9, 1.0, v10
	v_add_f32_e32 v10, 1.0, v11
	v_mul_f32_e32 v11, 0xbfb8aa3b, v32
	v_exp_f32_e32 v11, v11
	v_min_f32_e32 v9, 0x7149f2ca, v9
	v_min_f32_e32 v10, 0x7149f2ca, v10
	v_cvt_pk_bf16_f32 v9, v9, v10
	v_add_f32_e32 v10, 1.0, v11
	v_add_f32_e32 v11, 1.0, v13
	v_mul_f32_e32 v13, 0xbfb8aa3b, v34
	v_mul_f32_e32 v14, 0xbfb8aa3b, v35
	v_exp_f32_e32 v13, v13
	v_exp_f32_e32 v14, v14
	v_min_f32_e32 v10, 0x7149f2ca, v10
	v_min_f32_e32 v11, 0x7149f2ca, v11
	v_cvt_pk_bf16_f32 v10, v10, v11
	v_add_f32_e32 v11, 1.0, v13
	v_add_f32_e32 v13, 1.0, v14
	v_min_f32_e32 v11, 0x7149f2ca, v11
	v_min_f32_e32 v13, 0x7149f2ca, v13
	v_add_u32_e32 v12, 0x2400, v142
	v_cvt_pk_bf16_f32 v11, v11, v13
	global_store_dwordx4 v12, v[8:11], s[54:55] sc0 sc1
	v_mul_f32_e32 v13, 0xbfb8aa3b, v25
	v_exp_f32_e32 v13, v13
	v_mul_f32_e32 v8, 0xbfb8aa3b, v28
	v_mul_f32_e32 v9, 0xbfb8aa3b, v29
	v_exp_f32_e32 v8, v8
	v_exp_f32_e32 v9, v9
	v_mul_f32_e32 v10, 0xbfb8aa3b, v30
	v_mul_f32_e32 v11, 0xbfb8aa3b, v31
	v_exp_f32_e32 v10, v10
	v_exp_f32_e32 v11, v11
	v_add_f32_e32 v8, 1.0, v8
	v_add_f32_e32 v9, 1.0, v9
	v_min_f32_e32 v8, 0x7149f2ca, v8
	v_min_f32_e32 v9, 0x7149f2ca, v9
	v_cvt_pk_bf16_f32 v8, v8, v9
	v_add_f32_e32 v9, 1.0, v10
	v_add_f32_e32 v10, 1.0, v11
	v_mul_f32_e32 v11, 0xbfb8aa3b, v24
	v_exp_f32_e32 v11, v11
	v_min_f32_e32 v9, 0x7149f2ca, v9
	v_min_f32_e32 v10, 0x7149f2ca, v10
	v_cvt_pk_bf16_f32 v9, v9, v10
	v_add_f32_e32 v10, 1.0, v11
	v_add_f32_e32 v11, 1.0, v13
	v_mul_f32_e32 v13, 0xbfb8aa3b, v26
	v_mul_f32_e32 v14, 0xbfb8aa3b, v27
	v_exp_f32_e32 v13, v13
	v_exp_f32_e32 v14, v14
	v_min_f32_e32 v10, 0x7149f2ca, v10
	v_min_f32_e32 v11, 0x7149f2ca, v11
	v_cvt_pk_bf16_f32 v10, v10, v11
	v_add_f32_e32 v11, 1.0, v13
	v_add_f32_e32 v13, 1.0, v14
	v_min_f32_e32 v11, 0x7149f2ca, v11
	v_min_f32_e32 v13, 0x7149f2ca, v13
	v_add_u32_e32 v12, 0x2c00, v142
	v_cvt_pk_bf16_f32 v11, v11, v13
	global_store_dwordx4 v12, v[8:11], s[54:55] sc0 sc1
	v_mul_f32_e32 v13, 0xbfb8aa3b, v17
	v_exp_f32_e32 v13, v13
	v_mul_f32_e32 v8, 0xbfb8aa3b, v20
	v_mul_f32_e32 v9, 0xbfb8aa3b, v21
	v_exp_f32_e32 v8, v8
	v_exp_f32_e32 v9, v9
	v_mul_f32_e32 v10, 0xbfb8aa3b, v22
	v_mul_f32_e32 v11, 0xbfb8aa3b, v23
	v_exp_f32_e32 v10, v10
	v_exp_f32_e32 v11, v11
	v_add_f32_e32 v8, 1.0, v8
	v_add_f32_e32 v9, 1.0, v9
	v_min_f32_e32 v8, 0x7149f2ca, v8
	v_min_f32_e32 v9, 0x7149f2ca, v9
	v_cvt_pk_bf16_f32 v8, v8, v9
	v_add_f32_e32 v9, 1.0, v10
	v_add_f32_e32 v10, 1.0, v11
	v_mul_f32_e32 v11, 0xbfb8aa3b, v16
	v_exp_f32_e32 v11, v11
	v_mul_f32_e32 v4, 0xbfb8aa3b, v4
	v_mul_f32_e32 v5, 0xbfb8aa3b, v5
	v_exp_f32_e32 v4, v4
	v_exp_f32_e32 v5, v5
	v_min_f32_e32 v9, 0x7149f2ca, v9
	v_min_f32_e32 v10, 0x7149f2ca, v10
	v_mul_f32_e32 v6, 0xbfb8aa3b, v6
	v_mul_f32_e32 v7, 0xbfb8aa3b, v7
	v_mul_f32_e32 v0, 0xbfb8aa3b, v0
	v_mul_f32_e32 v1, 0xbfb8aa3b, v1
	v_cvt_pk_bf16_f32 v9, v9, v10
	v_add_f32_e32 v10, 1.0, v11
	v_add_f32_e32 v11, 1.0, v13
	v_mul_f32_e32 v13, 0xbfb8aa3b, v18
	v_mul_f32_e32 v14, 0xbfb8aa3b, v19
	v_exp_f32_e32 v6, v6
	v_exp_f32_e32 v7, v7
	v_exp_f32_e32 v0, v0
	v_exp_f32_e32 v1, v1
	v_exp_f32_e32 v13, v13
	v_exp_f32_e32 v14, v14
	v_mul_f32_e32 v2, 0xbfb8aa3b, v2
	v_mul_f32_e32 v3, 0xbfb8aa3b, v3
	v_add_f32_e32 v4, 1.0, v4
	v_add_f32_e32 v5, 1.0, v5
	v_exp_f32_e32 v2, v2
	v_exp_f32_e32 v3, v3
	v_min_f32_e32 v4, 0x7149f2ca, v4
	v_min_f32_e32 v5, 0x7149f2ca, v5
	v_min_f32_e32 v10, 0x7149f2ca, v10
	v_min_f32_e32 v11, 0x7149f2ca, v11
	v_cvt_pk_bf16_f32 v4, v4, v5
	v_add_f32_e32 v5, 1.0, v6
	v_add_f32_e32 v6, 1.0, v7
	v_add_f32_e32 v0, 1.0, v0
	v_add_f32_e32 v1, 1.0, v1
	v_cvt_pk_bf16_f32 v10, v10, v11
	v_add_f32_e32 v11, 1.0, v13
	v_add_f32_e32 v13, 1.0, v14
	v_min_f32_e32 v5, 0x7149f2ca, v5
	v_min_f32_e32 v6, 0x7149f2ca, v6
	v_min_f32_e32 v0, 0x7149f2ca, v0
	v_min_f32_e32 v1, 0x7149f2ca, v1
	v_min_f32_e32 v11, 0x7149f2ca, v11
	v_min_f32_e32 v13, 0x7149f2ca, v13
	v_cvt_pk_bf16_f32 v5, v5, v6
	v_cvt_pk_bf16_f32 v6, v0, v1
	v_add_f32_e32 v0, 1.0, v2
	v_add_f32_e32 v1, 1.0, v3
	v_add_u32_e32 v12, 0x3400, v142
	v_cvt_pk_bf16_f32 v11, v11, v13
	v_min_f32_e32 v0, 0x7149f2ca, v0
	v_min_f32_e32 v1, 0x7149f2ca, v1
	global_store_dwordx4 v12, v[8:11], s[54:55] sc0 sc1
	v_cvt_pk_bf16_f32 v7, v0, v1
	s_nop 0
	v_add_u32_e32 v8, 0x3c00, v142
	global_store_dwordx4 v8, v[4:7], s[54:55] sc0 sc1
